# conv loops: raw LDS tile double-buffered (address xor 0x8000 per unit), loop-end workgroup barrier removed (1 barrier per unit instead of 2)
# speedup vs baseline: 1.0013x; 1.0013x over previous
; #define LAS __attribute__((address_space(3)))
; #define LDS_SYNC() do { asm volatile("s_waitcnt lgkmcnt(0)" ::: "memory"); __builtin_amdgcn_s_barrier(); asm volatile("" ::: "memory"); } while (0)
; __device__ __forceinline__ void ph_conv_inplace(lds_u8* lds, bf16_t* XT, const float* convw, const bf16_t* halo, int norm_mode) {
;     ...
;         *(LAS vu4*)(raw + ((tid >> 4) + 2) * 128 + g8 * 8) = pb0; *(LAS vu4*)(raw + ((tid >> 4) + 34) * 128 + g8 * 8) = pb1;
;     ...
;         { const size_t bs = (((size_t)tt * 768 + cb * 16 + g8) * 64 + (tid >> 4)) * 8; *(vu4*)(XT + bs) = outv[0]; *(vu4*)(XT + bs + 32 * 8) = outv[1]; }
;         LDS_SYNC();
;     }
.LBB0_365:
	s_mul_hi_i32 s20, s22, 0x300
	s_mul_i32 s21, s22, 0x300
	s_mulk_i32 s22, 0xfd00
	s_add_i32 s22, s34, s22
	s_ashr_i32 s23, s22, 31
	s_add_u32 s21, s21, s22
	s_addc_u32 s20, s20, s23
	v_cvt_pk_bf16_f32 v27, v14, v15
	v_mov_b32_e32 v15, s20
	v_or_b32_e32 v14, s21, v1
	v_lshlrev_b64 v[14:15], 10, v[14:15]
	v_cvt_pk_bf16_f32 v22, v64, v65
	v_cvt_pk_bf16_f32 v23, v66, v67
	v_cvt_pk_bf16_f32 v24, v68, v69
	v_cvt_pk_bf16_f32 v25, v70, v71
	v_lshl_add_u64 v[14:15], v[62:63], 0, v[14:15]
	v_cvt_pk_bf16_f32 v26, v20, v21
	v_cvt_pk_bf16_f32 v28, v16, v17
	v_cvt_pk_bf16_f32 v29, v18, v19
	global_store_dwordx4 v[14:15], v[22:25], off
	global_store_dwordx4 v[14:15], v[26:29], off offset:512
	v_xor_b32_e32 v77, 0x8000, v77
	v_xor_b32_e32 v78, 0x8000, v78
	s_add_i32 s31, s31, s33
	s_add_i32 s34, s34, s35
	s_andn2_b64 vcc, exec, s[16:17]
	s_mov_b32 s44, s43
	s_cbranch_vccz .LBB0_386

; #define LAS __attribute__((address_space(3)))
; #define LDS_SYNC() do { asm volatile("s_waitcnt lgkmcnt(0)" ::: "memory"); __builtin_amdgcn_s_barrier(); asm volatile("" ::: "memory"); } while (0)
; __device__ __forceinline__ float silu_f(float x) { return x * __builtin_amdgcn_rcpf(1.0f + __expf(-x)); }
; __device__ __forceinline__ void ph_conv_inplace(lds_u8* lds, bf16_t* XT, const float* convw, const bf16_t* halo, int norm_mode) {
;     ...
;         LDS_SYNC();
;         vu4 outv[2];
; #pragma unroll
;         for (int i = 0; i < 2; ++i) { const int r = (tid >> 4) + 32 * i; float acc[8];
; #pragma unroll
;             for (int j = 0; j < 8; ++j) acc[j] = 0.f;
; #pragma unroll
;             for (int tap = 0; tap < 5; ++tap) { float xv[8]; unpack8(*(const LAS vu4*)(raw + (r + tap) * 128 + g8 * 8), xv);
; #pragma unroll
;                 for (int j = 0; j < 8; ++j) acc[j] += cw[tap][j] * xv[j]; }
;             float ss = 0.f;
; #pragma unroll
;             for (int j = 0; j < 8; ++j) { acc[j] = silu_f(acc[j]); ss += acc[j] * acc[j]; }
.LBB0_2002:
	s_waitcnt lgkmcnt(0)
	s_barrier
	ds_read_b128 v[76:79], v73
	ds_read_b128 v[80:83], v73 offset:256
	ds_read_b128 v[84:87], v73 offset:512
	ds_read_b128 v[58:61], v73 offset:768
	ds_read_b128 v[54:57], v73 offset:1024
	ds_read_b128 v[88:91], v73 offset:8192
	s_waitcnt lgkmcnt(5)
	v_lshlrev_b32_e32 v92, 16, v76
	v_and_b32_e32 v93, 0xffff0000, v76
	v_lshlrev_b32_e32 v76, 16, v77
	v_and_b32_e32 v77, 0xffff0000, v77
	s_waitcnt lgkmcnt(4)
	v_lshlrev_b32_e32 v94, 16, v80
	v_and_b32_e32 v95, 0xffff0000, v80
	v_lshlrev_b32_e32 v80, 16, v81
	v_and_b32_e32 v81, 0xffff0000, v81
	s_waitcnt lgkmcnt(3)
	v_lshlrev_b32_e32 v96, 16, v84
	v_and_b32_e32 v97, 0xffff0000, v84
	v_lshlrev_b32_e32 v84, 16, v85
	v_and_b32_e32 v85, 0xffff0000, v85
	s_waitcnt lgkmcnt(2)
	v_lshlrev_b32_e32 v98, 16, v58
	v_and_b32_e32 v99, 0xffff0000, v58
	v_lshlrev_b32_e32 v58, 16, v59
	v_and_b32_e32 v59, 0xffff0000, v59
	s_waitcnt lgkmcnt(1)
	v_lshlrev_b32_e32 v100, 16, v54
	v_and_b32_e32 v101, 0xffff0000, v54
	v_lshlrev_b32_e32 v54, 16, v55
	v_and_b32_e32 v55, 0xffff0000, v55
	v_lshlrev_b32_e32 v102, 16, v78
	v_and_b32_e32 v103, 0xffff0000, v78
	v_lshlrev_b32_e32 v104, 16, v82
	v_and_b32_e32 v105, 0xffff0000, v82
	v_lshlrev_b32_e32 v106, 16, v86
	v_and_b32_e32 v107, 0xffff0000, v86
	s_add_i32 s42, s37, s42
	s_ashr_i32 s45, s42, 31
	s_add_u32 s42, s44, s42
	s_addc_u32 s43, s43, s45
	s_add_i32 s27, s27, s28
	s_andn2_b64 vcc, exec, s[12:13]
	s_mov_b32 s37, s39
	s_mov_b32 s40, s38
	s_waitcnt vmcnt(11)
	v_pk_fma_f32 v[102:103], v[14:15], v[102:103], 0 op_sel_hi:[1,1,0]
	s_waitcnt vmcnt(10)
	v_pk_fma_f32 v[76:77], v[36:37], v[76:77], 0 op_sel_hi:[1,1,0]
	v_pk_fma_f32 v[92:93], v[34:35], v[92:93], 0 op_sel_hi:[1,1,0]
	s_waitcnt vmcnt(9)
	v_pk_fma_f32 v[76:77], v[40:41], v[80:81], v[76:77]
	v_pk_fma_f32 v[92:93], v[38:39], v[94:95], v[92:93]
	s_waitcnt vmcnt(8)
	v_pk_fma_f32 v[80:81], v[18:19], v[104:105], v[102:103]
	s_waitcnt vmcnt(7)
	v_pk_fma_f32 v[76:77], v[44:45], v[84:85], v[76:77]
	v_pk_fma_f32 v[92:93], v[42:43], v[96:97], v[92:93]
	s_waitcnt lgkmcnt(0)
	v_lshlrev_b32_e32 v94, 16, v88
	v_and_b32_e32 v95, 0xffff0000, v88
	v_pk_fma_f32 v[34:35], v[34:35], v[94:95], 0 op_sel_hi:[1,1,0]
	s_waitcnt vmcnt(6)
	v_pk_fma_f32 v[58:59], v[48:49], v[58:59], v[76:77]
	v_pk_fma_f32 v[84:85], v[46:47], v[98:99], v[92:93]
	v_lshlrev_b32_e32 v92, 16, v60
	v_and_b32_e32 v93, 0xffff0000, v60
	s_waitcnt vmcnt(5)
	v_pk_fma_f32 v[54:55], v[52:53], v[54:55], v[58:59]
	s_nop 0
	v_mul_f32_e32 v78, 0xbfb8aa3b, v54
	v_mul_f32_e32 v82, 0xbfb8aa3b, v55
	v_exp_f32_e32 v78, v78
	s_waitcnt vmcnt(4)
	v_pk_fma_f32 v[80:81], v[30:31], v[106:107], v[80:81]
	v_exp_f32_e32 v82, v82
	s_waitcnt vmcnt(3)
	v_pk_fma_f32 v[80:81], v[26:27], v[92:93], v[80:81]
	v_lshlrev_b32_e32 v92, 16, v56
	v_and_b32_e32 v93, 0xffff0000, v56
	s_waitcnt vmcnt(2)
	v_pk_fma_f32 v[80:81], v[22:23], v[92:93], v[80:81]
	v_add_f32_e32 v78, 1.0, v78
	v_mul_f32_e32 v60, 0xbfb8aa3b, v81
	v_exp_f32_e32 v60, v60
	v_pk_fma_f32 v[76:77], v[50:51], v[100:101], v[84:85]
	v_add_f32_e32 v82, 1.0, v82
	v_rcp_f32_e32 v84, v78
	v_lshlrev_b32_e32 v78, 16, v79
	v_and_b32_e32 v79, 0xffff0000, v79
	v_rcp_f32_e32 v85, v82
	v_pk_fma_f32 v[78:79], v[16:17], v[78:79], 0 op_sel_hi:[1,1,0]
	v_lshlrev_b32_e32 v82, 16, v83
	v_and_b32_e32 v83, 0xffff0000, v83
	v_pk_fma_f32 v[78:79], v[20:21], v[82:83], v[78:79]
	v_lshlrev_b32_e32 v82, 16, v87
	v_and_b32_e32 v83, 0xffff0000, v87
	v_add_f32_e32 v86, 1.0, v60
	v_pk_fma_f32 v[78:79], v[32:33], v[82:83], v[78:79]
	v_lshlrev_b32_e32 v60, 16, v61
	v_and_b32_e32 v61, 0xffff0000, v61
	v_pk_fma_f32 v[60:61], v[28:29], v[60:61], v[78:79]
	v_lshlrev_b32_e32 v78, 16, v57
	v_and_b32_e32 v79, 0xffff0000, v57
	v_pk_fma_f32 v[60:61], v[24:25], v[78:79], v[60:61]
	v_mul_f32_e32 v58, 0xbfb8aa3b, v76
	v_mul_f32_e32 v59, 0xbfb8aa3b, v77
	v_mul_f32_e32 v57, 0xbfb8aa3b, v60
	v_exp_f32_e32 v58, v58
	v_exp_f32_e32 v59, v59
	v_mul_f32_e32 v56, 0xbfb8aa3b, v80
	v_exp_f32_e32 v78, v57
	v_mul_f32_e32 v57, 0xbfb8aa3b, v61
	v_exp_f32_e32 v56, v56
	v_exp_f32_e32 v79, v57
	v_add_f32_e32 v58, 1.0, v58
	v_add_f32_e32 v59, 1.0, v59
	v_rcp_f32_e32 v58, v58
	v_rcp_f32_e32 v59, v59
	v_add_f32_e32 v56, 1.0, v56
	v_add_f32_e32 v78, 1.0, v78
	v_add_f32_e32 v79, 1.0, v79
	v_rcp_f32_e32 v56, v56
	v_rcp_f32_e32 v57, v86
	v_rcp_f32_e32 v78, v78
	v_rcp_f32_e32 v79, v79
	v_pk_mul_f32 v[58:59], v[76:77], v[58:59]
	v_pk_mul_f32 v[76:77], v[54:55], v[84:85]
	v_pk_mul_f32 v[56:57], v[80:81], v[56:57]
	v_pk_mul_f32 v[92:93], v[60:61], v[78:79]
	v_cvt_pk_bf16_f32 v54, v58, v59
	v_cvt_pk_bf16_f32 v55, v76, v77
	ds_read_b128 v[58:61], v73 offset:8448
	ds_read_b128 v[76:79], v73 offset:8704
	ds_read_b128 v[80:83], v73 offset:8960
	ds_read_b128 v[84:87], v73 offset:9216
	v_cvt_pk_bf16_f32 v56, v56, v57
	s_waitcnt lgkmcnt(3)
; #define LAS __attribute__((address_space(3)))
; #define LDS_SYNC() do { asm volatile("s_waitcnt lgkmcnt(0)" ::: "memory"); __builtin_amdgcn_s_barrier(); asm volatile("" ::: "memory"); } while (0)
; __device__ __forceinline__ vu4 pack8(const float (&f)[8]) { vu4 w; w.x = pg8::cvt_pk_bf16(f[0], f[1]); w.y = pg8::cvt_pk_bf16(f[2], f[3]); w.z = pg8::cvt_pk_bf16(f[4], f[5]); w.w = pg8::cvt_pk_bf16(f[6], f[7]); return w; }
; __device__ __forceinline__ float silu_f(float x) { return x * __builtin_amdgcn_rcpf(1.0f + __expf(-x)); }
; __device__ __forceinline__ void ph_conv_inplace(lds_u8* lds, bf16_t* XT, const float* convw, const bf16_t* halo, int norm_mode) {
;     ...
;         for (int i = 0; i < 2; ++i) { const int r = (tid >> 4) + 32 * i; float acc[8];
; #pragma unroll
;             for (int j = 0; j < 8; ++j) acc[j] = 0.f;
; #pragma unroll
;             for (int tap = 0; tap < 5; ++tap) { float xv[8]; unpack8(*(const LAS vu4*)(raw + (r + tap) * 128 + g8 * 8), xv);
; #pragma unroll
;                 for (int j = 0; j < 8; ++j) acc[j] += cw[tap][j] * xv[j]; }
;             float ss = 0.f;
; #pragma unroll
;             for (int j = 0; j < 8; ++j) { acc[j] = silu_f(acc[j]); ss += acc[j] * acc[j]; }
;             if (norm_mode == 1 && cb < 32) { ss += __shfl_xor(ss, 1); ss += __shfl_xor(ss, 2); ss += __shfl_xor(ss, 4); ss += __shfl_xor(ss, 8);
;                 const float sc = rsqrtf(ss + EPSN) * (cb < 16 ? 0.08838834764831845f : 1.0f);
; #pragma unroll
;                 for (int j = 0; j < 8; ++j) acc[j] *= sc; }
;             outv[i] = pack8(acc); }
;         { const size_t bs = (((size_t)tt * 768 + cb * 16 + g8) * 64 + (tid >> 4)) * 8; *(vu4*)(XT + bs) = outv[0]; *(vu4*)(XT + bs + 32 * 8) = outv[1]; }
;         LDS_SYNC();
;     }
	v_lshlrev_b32_e32 v94, 16, v58
	v_and_b32_e32 v95, 0xffff0000, v58
	v_pk_fma_f32 v[34:35], v[38:39], v[94:95], v[34:35]
	s_waitcnt lgkmcnt(2)
	v_lshlrev_b32_e32 v38, 16, v76
	v_and_b32_e32 v39, 0xffff0000, v76
	v_pk_fma_f32 v[34:35], v[42:43], v[38:39], v[34:35]
	v_lshlrev_b32_e32 v42, 16, v89
	v_and_b32_e32 v43, 0xffff0000, v89
	v_pk_fma_f32 v[36:37], v[36:37], v[42:43], 0 op_sel_hi:[1,1,0]
	v_lshlrev_b32_e32 v42, 16, v59
	v_and_b32_e32 v43, 0xffff0000, v59
	v_pk_fma_f32 v[36:37], v[40:41], v[42:43], v[36:37]
	v_lshlrev_b32_e32 v42, 16, v90
	v_and_b32_e32 v43, 0xffff0000, v90
	v_pk_fma_f32 v[14:15], v[14:15], v[42:43], 0 op_sel_hi:[1,1,0]
	v_lshlrev_b32_e32 v42, 16, v60
	v_and_b32_e32 v43, 0xffff0000, v60
	v_pk_fma_f32 v[14:15], v[18:19], v[42:43], v[14:15]
	v_lshlrev_b32_e32 v18, 16, v78
	v_and_b32_e32 v19, 0xffff0000, v78
	v_pk_fma_f32 v[14:15], v[30:31], v[18:19], v[14:15]
	s_waitcnt lgkmcnt(1)
	v_lshlrev_b32_e32 v18, 16, v82
	v_and_b32_e32 v19, 0xffff0000, v82
	v_pk_fma_f32 v[14:15], v[26:27], v[18:19], v[14:15]
	s_waitcnt lgkmcnt(0)
	v_lshlrev_b32_e32 v18, 16, v86
	v_and_b32_e32 v19, 0xffff0000, v86
	v_pk_fma_f32 v[14:15], v[22:23], v[18:19], v[14:15]
	v_lshlrev_b32_e32 v22, 16, v91
	v_and_b32_e32 v23, 0xffff0000, v91
	v_pk_fma_f32 v[16:17], v[16:17], v[22:23], 0 op_sel_hi:[1,1,0]
	v_lshlrev_b32_e32 v22, 16, v61
	v_and_b32_e32 v23, 0xffff0000, v61
	v_pk_fma_f32 v[16:17], v[20:21], v[22:23], v[16:17]
	v_lshlrev_b32_e32 v20, 16, v79
	v_and_b32_e32 v21, 0xffff0000, v79
	v_pk_fma_f32 v[16:17], v[32:33], v[20:21], v[16:17]
	v_lshlrev_b32_e32 v20, 16, v83
	v_and_b32_e32 v21, 0xffff0000, v83
	v_lshlrev_b32_e32 v40, 16, v77
	v_and_b32_e32 v41, 0xffff0000, v77
	v_pk_fma_f32 v[16:17], v[28:29], v[20:21], v[16:17]
	v_lshlrev_b32_e32 v20, 16, v87
	v_and_b32_e32 v21, 0xffff0000, v87
	v_lshlrev_b32_e32 v38, 16, v80
	v_and_b32_e32 v39, 0xffff0000, v80
	v_pk_fma_f32 v[36:37], v[44:45], v[40:41], v[36:37]
	v_lshlrev_b32_e32 v40, 16, v81
	v_and_b32_e32 v41, 0xffff0000, v81
	v_mul_f32_e32 v18, 0xbfb8aa3b, v14
	v_mul_f32_e32 v19, 0xbfb8aa3b, v15
	v_pk_fma_f32 v[16:17], v[24:25], v[20:21], v[16:17]
	v_pk_fma_f32 v[34:35], v[46:47], v[38:39], v[34:35]
	v_lshlrev_b32_e32 v38, 16, v84
	v_and_b32_e32 v39, 0xffff0000, v84
	v_pk_fma_f32 v[36:37], v[48:49], v[40:41], v[36:37]
	v_lshlrev_b32_e32 v40, 16, v85
	v_and_b32_e32 v41, 0xffff0000, v85
	v_exp_f32_e32 v18, v18
	v_exp_f32_e32 v19, v19
	v_mul_f32_e32 v20, 0xbfb8aa3b, v16
	v_mul_f32_e32 v21, 0xbfb8aa3b, v17
	v_pk_fma_f32 v[34:35], v[50:51], v[38:39], v[34:35]
	v_pk_fma_f32 v[36:37], v[52:53], v[40:41], v[36:37]
	v_exp_f32_e32 v20, v20
	v_exp_f32_e32 v21, v21
	v_mul_f32_e32 v38, 0xbfb8aa3b, v34
	v_mul_f32_e32 v39, 0xbfb8aa3b, v35
	v_mul_f32_e32 v40, 0xbfb8aa3b, v36
	v_mul_f32_e32 v41, 0xbfb8aa3b, v37
	v_exp_f32_e32 v38, v38
	v_exp_f32_e32 v39, v39
	v_exp_f32_e32 v40, v40
	v_exp_f32_e32 v41, v41
	v_add_f32_e32 v18, 1.0, v18
	v_add_f32_e32 v19, 1.0, v19
	v_rcp_f32_e32 v18, v18
	v_rcp_f32_e32 v19, v19
	v_add_f32_e32 v20, 1.0, v20
	v_add_f32_e32 v21, 1.0, v21
	v_rcp_f32_e32 v20, v20
	v_rcp_f32_e32 v21, v21
	v_add_f32_e32 v38, 1.0, v38
	v_add_f32_e32 v39, 1.0, v39
	v_add_f32_e32 v40, 1.0, v40
	v_add_f32_e32 v41, 1.0, v41
	v_rcp_f32_e32 v38, v38
	v_rcp_f32_e32 v39, v39
	v_rcp_f32_e32 v40, v40
	v_rcp_f32_e32 v41, v41
	v_pk_mul_f32 v[18:19], v[14:15], v[18:19]
	v_pk_mul_f32 v[20:21], v[16:17], v[20:21]
	v_cvt_pk_bf16_f32 v16, v18, v19
	v_mov_b32_e32 v19, s43
	v_or_b32_e32 v18, s42, v1
	v_lshlrev_b64 v[18:19], 10, v[18:19]
	v_cvt_pk_bf16_f32 v57, v92, v93
	v_pk_mul_f32 v[22:23], v[34:35], v[38:39]
	v_pk_mul_f32 v[24:25], v[36:37], v[40:41]
	v_lshl_add_u64 v[18:19], v[70:71], 0, v[18:19]
	v_cvt_pk_bf16_f32 v14, v22, v23
	v_cvt_pk_bf16_f32 v15, v24, v25
	v_cvt_pk_bf16_f32 v17, v20, v21
	global_store_dwordx4 v[18:19], v[54:57], off
	global_store_dwordx4 v[18:19], v[14:17], off offset:512
	v_xor_b32_e32 v73, 0x8000, v73
	v_xor_b32_e32 v74, 0x8000, v74
	s_cbranch_vccz .LBB0_2019
